# opt30: at the grid barrier a non-leader workgroup polls its XCD's arrival counter and issues its L1 invalidate once every local workgroup has arrived (the XCD's L2 is idle then), then waits for the re
# speedup vs baseline: 1.0335x; 1.0008x over previous
.Lmy_xs_23:
	v_mov_b32_e32 v0, 0x1000
	global_load_dword v0, v0, s[4:5] offset:1024 sc1
	s_waitcnt vmcnt(0)
	v_cmp_ge_u32_e32 vcc, v0, v2
	s_cbranch_vccnz .Lmy_xsd_23
	s_sleep 1
	s_branch .Lmy_xs_23
.Lmy_xsd_23:
	buffer_inv sc1
	s_waitcnt lgkmcnt(0)
	v_mov_b32_e32 v0, 0x2000
	global_load_dword v0, v0, s[4:5] offset:1024 sc1
	s_add_u32 s14, s4, 0x2400
	s_addc_u32 s15, s5, 0
	s_waitcnt vmcnt(0)
	v_cmp_eq_u32_e32 vcc, v0, v1
	s_and_saveexec_b64 s[8:9], vcc
	s_cbranch_execz .LBB0_165
	s_add_u32 s10, s70, 0x4200
	s_addc_u32 s11, s71, 0
	s_mov_b32 s3, 1
	s_mov_b64 s[16:17], 0
	v_mov_b32_e32 v0, 0
	s_branch .LBB0_156

.Lmy_xsd_22:
	buffer_inv sc1
	s_waitcnt lgkmcnt(0)
	v_mov_b32_e32 v0, 0x2000
	global_load_dword v0, v0, s[4:5] offset:1024 sc1
	s_add_u32 s20, s4, 0x2400
	s_addc_u32 s21, s5, 0
	s_waitcnt vmcnt(0)
	v_cmp_eq_u32_e32 vcc, v0, v1
	s_and_saveexec_b64 s[8:9], vcc
	s_cbranch_execz .LBB0_281
	s_add_u32 s10, s70, 0x4200
	s_addc_u32 s11, s71, 0
	s_mov_b32 s3, 1
	s_mov_b64 s[22:23], 0
	v_mov_b32_e32 v0, 0
	s_branch .LBB0_272

.Lmy_xsd_21:
	buffer_inv sc1
	s_waitcnt lgkmcnt(0)
	v_mov_b32_e32 v0, 0x2000
	global_load_dword v0, v0, s[4:5] offset:1024 sc1
	s_add_u32 s22, s4, 0x2400
	s_addc_u32 s23, s5, 0
	s_waitcnt vmcnt(0)
	v_cmp_eq_u32_e32 vcc, v0, v1
	s_and_saveexec_b64 s[8:9], vcc
	s_cbranch_execz .LBB0_343
	s_add_u32 s10, s70, 0x4200
	s_addc_u32 s11, s71, 0
	s_mov_b32 s3, 1
	s_mov_b64 s[26:27], 0
	v_mov_b32_e32 v0, 0
	s_branch .LBB0_334

.Lmy_xsd_11:
	buffer_inv sc1
	s_waitcnt lgkmcnt(0)
	v_mov_b32_e32 v0, 0x2000
	global_load_dword v0, v0, s[4:5] offset:1024 sc1
	s_add_u32 s26, s4, 0x2400
	s_addc_u32 s27, s5, 0
	s_waitcnt vmcnt(0)
	v_cmp_eq_u32_e32 vcc, v0, v1
	s_and_saveexec_b64 s[10:11], vcc
	s_cbranch_execz .LBB0_1378
	s_add_u32 s22, s70, 0x4200
	s_addc_u32 s23, s71, 0
	s_mov_b32 s3, 1
	s_mov_b64 s[28:29], 0
	v_mov_b32_e32 v0, 0
	s_branch .LBB0_1369

.Lmy_xsd_4:
	buffer_inv sc1
	s_waitcnt lgkmcnt(0)
	v_mov_b32_e32 v0, 0x2000
	global_load_dword v0, v0, s[4:5] offset:1024 sc1
	s_add_u32 s22, s4, 0x2400
	s_addc_u32 s23, s5, 0
	s_waitcnt vmcnt(0)
	v_cmp_eq_u32_e32 vcc, v0, v1
	s_and_saveexec_b64 s[8:9], vcc
	s_cbranch_execz .LBB0_1958
	s_add_u32 s10, s70, 0x4200
	s_addc_u32 s11, s71, 0
	s_mov_b32 s3, 1
	s_mov_b64 s[24:25], 0
	v_mov_b32_e32 v0, 0
	s_branch .LBB0_1949

.Lmy_xsd_2:
	buffer_inv sc1
	s_waitcnt lgkmcnt(0)
	v_mov_b32_e32 v0, 0x2000
	global_load_dword v0, v0, s[4:5] offset:1024 sc1
	s_add_u32 s18, s4, 0x2400
	s_addc_u32 s19, s5, 0
	s_waitcnt vmcnt(0)
	v_cmp_eq_u32_e32 vcc, v0, v1
	s_and_saveexec_b64 s[8:9], vcc
	s_cbranch_execz .LBB0_2130
	s_add_u32 s10, s70, 0x4200
	s_addc_u32 s11, s71, 0
	s_mov_b32 s3, 1
	s_mov_b64 s[20:21], 0
	v_mov_b32_e32 v0, 0
	s_branch .LBB0_2121

.Lmy_xs_1:
	v_mov_b32_e32 v0, 0x1000
	global_load_dword v0, v0, s[2:3] offset:1024 sc1
	s_waitcnt vmcnt(0)
	v_cmp_ge_u32_e32 vcc, v0, v2
	s_cbranch_vccnz .Lmy_xsd_1
	s_sleep 1
	s_branch .Lmy_xs_1
.Lmy_xsd_1:
	buffer_inv sc1
	s_waitcnt lgkmcnt(0)
	v_mov_b32_e32 v0, 0x2000
	global_load_dword v0, v0, s[2:3] offset:1024 sc1
	s_add_u32 s10, s2, 0x2400
	s_addc_u32 s11, s3, 0
	s_waitcnt vmcnt(0)
	v_cmp_eq_u32_e32 vcc, v0, v1
	s_and_saveexec_b64 s[6:7], vcc
	s_cbranch_execz .LBB0_2213
	s_add_u32 s8, s70, 0x4200
	s_addc_u32 s9, s71, 0
	s_mov_b32 s22, 1
	s_mov_b64 s[12:13], 0
	v_mov_b32_e32 v0, 0
	s_branch .LBB0_2204
